# row-sum v_pk_add_f32 chains in both attention loops split into scalar v_add_f32 pairs (hazard nops dropped), bit-identical
# speedup vs baseline: 1.0017x; 1.0017x over previous
; #define LAS __attribute__((address_space(3)))
; __device__ __forceinline__ void finishSM(f32x16& p0, f32x16& p1, float alpha, float& l_reg, bf16x8& pa0, bf16x8& pa1, bf16x8& pa2, bf16x8& pa3) {
; #pragma unroll
;     for (int r = 0; r < 16; ++r) p1[r] = __builtin_amdgcn_exp2f(p1[r]);
;     typedef float f32x2 __attribute__((ext_vector_type(2)));
;     f32x2 s2 = (f32x2){p0[0], p0[1]};
; #pragma unroll
;     for (int r = 2; r < 16; r += 2) s2 += (f32x2){p0[r], p0[r + 1]};
; #pragma unroll
;     for (int r = 0; r < 16; r += 2) s2 += (f32x2){p1[r], p1[r + 1]};
;     float ps = s2.x + s2.y;
;     { auto rr = __builtin_amdgcn_permlane32_swap(__float_as_uint(ps), __float_as_uint(ps), false, false);
;       ps = __uint_as_float(rr[0]) + __uint_as_float(rr[1]); }
;     l_reg = l_reg * alpha + ps;
;     ...
;     PK4(p0, 0, pa0); PK4(p0, 8, pa1); PK4(p1, 0, pa2); PK4(p1, 8, pa3);
;     ...
; }
; template <int MODE> __device__ __forceinline__ void qkt(f32x16& p0, f32x16& p1, const LAS unsigned char* Kt, const LAS unsigned char* Krt, const bf16x8* qr, int r32, int hi, int comp) {
;     p0 = f32x16{}; p1 = f32x16{};
;     constexpr int NDN = MODE ? 8 : 4;
; #pragma unroll
;     for (int d0 = 0; d0 < NDN; ++d0) { const int cb = ((MODE ? 0 : comp * 64) + d0 * 16 + hi * 8) * 2;
;         const bf16x8 b0 = *(const LAS bf16x8*)(Kt + KSWZ(r32, cb));
;         const bf16x8 b1 = *(const LAS bf16x8*)(Kt + KSWZ(32 + r32, cb));
;         p0 = __builtin_amdgcn_mfma_f32_32x32x16_bf16(b0, qr[d0], p0, 0, 0, 0);
;         p1 = __builtin_amdgcn_mfma_f32_32x32x16_bf16(b1, qr[d0], p1, 0, 0, 0); }
.LBB0_543:
	v_add_u32_e32 v181, v180, v171
	ds_read_b128 v[96:99], v181
	ds_read_b128 v[112:115], v181 offset:8192
	v_add_u32_e32 v182, v180, v173
	v_add_u32_e32 v183, v180, v175
	v_add_u32_e32 v184, v180, v177
	ds_read_b128 v[188:191], v182
	ds_read_b128 v[192:195], v182 offset:8192
	ds_read_b128 v[200:203], v183
	ds_read_b128 v[204:207], v183 offset:8192
	ds_read_b128 v[208:211], v184
	ds_read_b128 v[212:215], v184 offset:8192
	v_exp_f32_e32 v196, v84
	v_exp_f32_e32 v197, v85
	v_add_f32_e32 v84, v64, v66
	v_add_f32_e32 v85, v65, v67
	s_waitcnt lgkmcnt(0)
	v_mfma_f32_32x32x16_bf16 v[96:111], v[96:99], v[140:143], v[216:231]
	v_add_f32_e64 v84, v68, v84
	v_add_f32_e64 v85, v69, v85
	v_exp_f32_e32 v80, v80
	v_add_f32_e32 v84, v70, v84
	v_add_f32_e32 v85, v71, v85
	v_exp_f32_e32 v81, v81
	v_add_f32_e32 v84, v72, v84
	v_add_f32_e32 v85, v73, v85
	v_exp_f32_e32 v82, v82
	v_exp_f32_e32 v83, v83
	v_mfma_f32_32x32x16_bf16 v[112:127], v[112:115], v[140:143], v[216:231]
	v_add_f32_e64 v84, v74, v84
	v_add_f32_e64 v85, v75, v85
	v_exp_f32_e32 v198, v86
	v_add_f32_e32 v84, v76, v84
	v_add_f32_e32 v85, v77, v85
	v_exp_f32_e32 v199, v87
	v_add_f32_e32 v84, v78, v84
	v_add_f32_e32 v85, v79, v85
	v_exp_f32_e32 v88, v88
	v_exp_f32_e32 v89, v89
	v_mfma_f32_32x32x16_bf16 v[96:111], v[188:191], v[136:139], v[96:111]
	v_add_f32_e64 v84, v80, v84
	v_add_f32_e64 v85, v81, v85
	v_exp_f32_e32 v90, v90
	v_exp_f32_e32 v91, v91
	v_add_f32_e32 v84, v82, v84
	v_add_f32_e32 v85, v83, v85
	v_exp_f32_e32 v92, v92
	v_exp_f32_e32 v93, v93
	v_add_f32_e32 v84, v196, v84
	v_add_f32_e32 v85, v197, v85
	v_mfma_f32_32x32x16_bf16 v[112:127], v[192:195], v[136:139], v[112:127]
	v_exp_f32_e32 v94, v94
	v_exp_f32_e32 v95, v95
	v_add_f32_e32 v84, v198, v84
	v_add_f32_e32 v85, v199, v85
	v_add_f32_e32 v84, v88, v84
	v_add_f32_e32 v85, v89, v85
	v_add_f32_e32 v84, v90, v84
	v_add_f32_e32 v85, v91, v85
	v_mfma_f32_32x32x16_bf16 v[96:111], v[200:203], v[132:135], v[96:111]
	v_add_f32_e64 v84, v92, v84
	v_add_f32_e64 v85, v93, v85
	v_add_f32_e64 v84, v94, v84
	v_add_f32_e64 v85, v95, v85
	v_add_f32_e64 v162, v84, v85
	v_add_f32_e64 v163, v85, v84
	v_cvt_pk_bf16_f32 v84, v64, v65
	v_cvt_pk_bf16_f32 v85, v66, v67
	v_mfma_f32_32x32x16_bf16 v[112:127], v[204:207], v[132:135], v[112:127]
	v_mov_b32_e32 v187, v162
	v_cvt_pk_bf16_f32 v86, v68, v69
	v_cvt_pk_bf16_f32 v87, v70, v71
	v_cvt_pk_bf16_f32 v72, v72, v73
	v_cvt_pk_bf16_f32 v73, v74, v75
	v_cvt_pk_bf16_f32 v74, v76, v77
	v_cvt_pk_bf16_f32 v75, v78, v79
	v_mfma_f32_32x32x16_bf16 v[96:111], v[208:211], v[128:131], v[96:111]
	v_cvt_pk_bf16_f32 v76, v80, v81
	v_cvt_pk_bf16_f32 v77, v82, v83
	v_cvt_pk_bf16_f32 v78, v196, v197
	v_cvt_pk_bf16_f32 v79, v198, v199
	v_cvt_pk_bf16_f32 v80, v88, v89
	v_cvt_pk_bf16_f32 v81, v90, v91
	v_cvt_pk_bf16_f32 v82, v92, v93
	v_mfma_f32_32x32x16_bf16 v[112:127], v[212:215], v[128:131], v[112:127]
	v_cvt_pk_bf16_f32 v83, v94, v95
	v_permlane32_swap_b32_e32 v162, v187
	s_andn2_b64 s[4:5], exec, s[62:63]
	s_andn2_b64 vcc, exec, s[62:63]
	s_cbranch_vccnz .LBB0_545
	s_waitcnt vmcnt(0) lgkmcnt(0)
	s_barrier

; #define LAS __attribute__((address_space(3)))
; __device__ __forceinline__ void finishSM(f32x16& p0, f32x16& p1, float alpha, float& l_reg, bf16x8& pa0, bf16x8& pa1, bf16x8& pa2, bf16x8& pa3) {
; #pragma unroll
;     for (int r = 0; r < 16; ++r) p1[r] = __builtin_amdgcn_exp2f(p1[r]);
;     typedef float f32x2 __attribute__((ext_vector_type(2)));
;     f32x2 s2 = (f32x2){p0[0], p0[1]};
; #pragma unroll
;     for (int r = 2; r < 16; r += 2) s2 += (f32x2){p0[r], p0[r + 1]};
; #pragma unroll
;     for (int r = 0; r < 16; r += 2) s2 += (f32x2){p1[r], p1[r + 1]};
;     float ps = s2.x + s2.y;
;     { auto rr = __builtin_amdgcn_permlane32_swap(__float_as_uint(ps), __float_as_uint(ps), false, false);
;       ps = __uint_as_float(rr[0]) + __uint_as_float(rr[1]); }
;     l_reg = l_reg * alpha + ps;
;     ...
;     PK4(p0, 0, pa0); PK4(p0, 8, pa1); PK4(p1, 0, pa2); PK4(p1, 8, pa3);
;     ...
; }
; template <int MODE> __device__ __forceinline__ void qkt(f32x16& p0, f32x16& p1, const LAS unsigned char* Kt, const LAS unsigned char* Krt, const bf16x8* qr, int r32, int hi, int comp) {
;     p0 = f32x16{}; p1 = f32x16{};
;     constexpr int NDN = MODE ? 8 : 4;
; #pragma unroll
;     for (int d0 = 0; d0 < NDN; ++d0) { const int cb = ((MODE ? 0 : comp * 64) + d0 * 16 + hi * 8) * 2;
;         const bf16x8 b0 = *(const LAS bf16x8*)(Kt + KSWZ(r32, cb));
;         const bf16x8 b1 = *(const LAS bf16x8*)(Kt + KSWZ(32 + r32, cb));
;         p0 = __builtin_amdgcn_mfma_f32_32x32x16_bf16(b0, qr[d0], p0, 0, 0, 0);
;         p1 = __builtin_amdgcn_mfma_f32_32x32x16_bf16(b1, qr[d0], p1, 0, 0, 0); }
.LBB0_555:
	ds_read_b128 v[80:83], v172 offset:49152
	ds_read_b128 v[84:87], v172 offset:57344
	ds_read_b128 v[190:193], v174 offset:49152
	ds_read_b128 v[194:197], v174 offset:57344
	v_exp_f32_e32 v112, v112
	v_exp_f32_e32 v113, v113
	s_waitcnt lgkmcnt(0)
	v_mfma_f32_32x32x16_bf16 v[96:111], v[80:83], v[140:143], v[216:231]
	v_exp_f32_e32 v114, v114
	v_exp_f32_e32 v115, v115
	v_exp_f32_e32 v122, v122
	v_exp_f32_e32 v123, v123
	v_exp_f32_e32 v124, v124
	v_exp_f32_e32 v125, v125
	v_exp_f32_e32 v126, v126
	v_mfma_f32_32x32x16_bf16 v[80:95], v[84:87], v[140:143], v[216:231]
	v_exp_f32_e32 v127, v127
	v_mfma_f32_32x32x16_bf16 v[96:111], v[190:193], v[136:139], v[96:111]
	v_mfma_f32_32x32x16_bf16 v[80:95], v[194:197], v[136:139], v[80:95]
	ds_read_b128 v[190:193], v176 offset:49152
	ds_read_b128 v[194:197], v176 offset:57344
	s_waitcnt lgkmcnt(0)
	v_mfma_f32_32x32x16_bf16 v[96:111], v[190:193], v[132:135], v[96:111]
	v_mfma_f32_32x32x16_bf16 v[80:95], v[194:197], v[132:135], v[80:95]
	ds_read_b128 v[190:193], v178 offset:49152
	ds_read_b128 v[194:197], v178 offset:57344
	s_waitcnt lgkmcnt(0)
	v_mfma_f32_32x32x16_bf16 v[96:111], v[190:193], v[128:131], v[96:111]
	v_exp_f32_e32 v190, v116
	v_exp_f32_e32 v191, v117
	v_add_f32_e32 v116, v64, v66
	v_add_f32_e32 v117, v65, v67
	v_exp_f32_e32 v192, v118
	v_add_f32_e32 v116, v68, v116
	v_add_f32_e32 v117, v69, v117
	v_exp_f32_e32 v193, v119
	v_add_f32_e32 v116, v70, v116
	v_add_f32_e32 v117, v71, v117
	v_mfma_f32_32x32x16_bf16 v[80:95], v[194:197], v[128:131], v[80:95]
	v_add_f32_e64 v116, v72, v116
	v_add_f32_e64 v117, v73, v117
	v_exp_f32_e32 v194, v120
	v_add_f32_e32 v116, v74, v116
	v_add_f32_e32 v117, v75, v117
	v_exp_f32_e32 v195, v121
	v_add_f32_e32 v116, v76, v116
	v_add_f32_e32 v117, v77, v117
	v_add_f32_e32 v116, v78, v116
	v_add_f32_e32 v117, v79, v117
	v_add_f32_e32 v116, v112, v116
	v_add_f32_e32 v117, v113, v117
	v_add_f32_e32 v116, v114, v116
	v_add_f32_e32 v117, v115, v117
	v_add_f32_e32 v116, v190, v116
	v_add_f32_e32 v117, v191, v117
	v_add_f32_e32 v116, v192, v116
	v_add_f32_e32 v117, v193, v117
	v_add_f32_e32 v116, v194, v116
	v_add_f32_e32 v117, v195, v117
	v_add_f32_e32 v116, v122, v116
	v_add_f32_e32 v117, v123, v117
	v_add_f32_e32 v116, v124, v116
	v_add_f32_e32 v117, v125, v117
	v_add_f32_e32 v116, v126, v116
	v_add_f32_e32 v117, v127, v117
	v_pk_add_f32 v[120:121], v[116:117], v[116:117] op_sel:[0,1] op_sel_hi:[1,0]
	v_cvt_pk_bf16_f32 v116, v64, v65
	v_cvt_pk_bf16_f32 v117, v66, v67
	v_cvt_pk_bf16_f32 v118, v68, v69
	v_cvt_pk_bf16_f32 v119, v70, v71
	v_cvt_pk_bf16_f32 v72, v72, v73
	s_nop 0
	v_mov_b32_e32 v121, v120
	v_cvt_pk_bf16_f32 v73, v74, v75
	v_cvt_pk_bf16_f32 v74, v76, v77
	v_cvt_pk_bf16_f32 v75, v78, v79
	v_cvt_pk_bf16_f32 v76, v112, v113
	v_cvt_pk_bf16_f32 v77, v114, v115
	v_cvt_pk_bf16_f32 v78, v190, v191
	v_cvt_pk_bf16_f32 v79, v192, v193
	v_cvt_pk_bf16_f32 v112, v194, v195
	v_cvt_pk_bf16_f32 v113, v122, v123
	v_cvt_pk_bf16_f32 v114, v124, v125
	v_cvt_pk_bf16_f32 v115, v126, v127
	s_nop 1
	v_permlane32_swap_b32_e32 v120, v121
	s_and_b64 vcc, exec, s[4:5]
	s_cbranch_vccnz .LBB0_557
	s_waitcnt vmcnt(0) lgkmcnt(0)
	s_barrier

; #define LAS __attribute__((address_space(3)))
; __device__ __forceinline__ void finishSM(f32x16& p0, f32x16& p1, float alpha, float& l_reg, bf16x8& pa0, bf16x8& pa1, bf16x8& pa2, bf16x8& pa3) {
; #pragma unroll
;     for (int r = 0; r < 16; ++r) p1[r] = __builtin_amdgcn_exp2f(p1[r]);
;     typedef float f32x2 __attribute__((ext_vector_type(2)));
;     f32x2 s2 = (f32x2){p0[0], p0[1]};
; #pragma unroll
;     for (int r = 2; r < 16; r += 2) s2 += (f32x2){p0[r], p0[r + 1]};
; #pragma unroll
;     for (int r = 0; r < 16; r += 2) s2 += (f32x2){p1[r], p1[r + 1]};
;     float ps = s2.x + s2.y;
;     { auto rr = __builtin_amdgcn_permlane32_swap(__float_as_uint(ps), __float_as_uint(ps), false, false);
;       ps = __uint_as_float(rr[0]) + __uint_as_float(rr[1]); }
;     l_reg = l_reg * alpha + ps;
;     ...
;     PK4(p0, 0, pa0); PK4(p0, 8, pa1); PK4(p1, 0, pa2); PK4(p1, 8, pa3);
;     ...
; }
; template <int MODE> __device__ __forceinline__ void qkt(f32x16& p0, f32x16& p1, const LAS unsigned char* Kt, const LAS unsigned char* Krt, const bf16x8* qr, int r32, int hi, int comp) {
;     p0 = f32x16{}; p1 = f32x16{};
;     constexpr int NDN = MODE ? 8 : 4;
; #pragma unroll
;     for (int d0 = 0; d0 < NDN; ++d0) { const int cb = ((MODE ? 0 : comp * 64) + d0 * 16 + hi * 8) * 2;
;         const bf16x8 b0 = *(const LAS bf16x8*)(Kt + KSWZ(r32, cb));
;         const bf16x8 b1 = *(const LAS bf16x8*)(Kt + KSWZ(32 + r32, cb));
;         p0 = __builtin_amdgcn_mfma_f32_32x32x16_bf16(b0, qr[d0], p0, 0, 0, 0);
;         p1 = __builtin_amdgcn_mfma_f32_32x32x16_bf16(b1, qr[d0], p1, 0, 0, 0); }
;     if constexpr (MODE == 1) {
; #pragma unroll
;         for (int d0 = 0; d0 < 4; ++d0) { const int cb = (d0 * 16 + hi * 8) * 2;
;             const bf16x8 b0 = *(const LAS bf16x8*)(Krt + KRSWZ(r32, cb));
;             const bf16x8 b1 = *(const LAS bf16x8*)(Krt + KRSWZ(32 + r32, cb));
;             p0 = __builtin_amdgcn_mfma_f32_32x32x16_bf16(b0, qr[8 + d0], p0, 0, 0, 0);
;             p1 = __builtin_amdgcn_mfma_f32_32x32x16_bf16(b1, qr[8 + d0], p1, 0, 0, 0); }
;     }
; }
.LBB0_602:
	v_add_u32_e32 v231, v229, v204
	ds_read_b128 v[96:99], v231
	ds_read_b128 v[100:103], v231 offset:8192
	v_add_u32_e32 v232, v229, v206
	ds_read_b128 v[234:237], v232
	ds_read_b128 v[238:241], v232 offset:8192
	v_add_u32_e32 v233, v229, v208
	s_waitcnt lgkmcnt(0)
	v_mfma_f32_32x32x16_bf16 v[112:127], v[96:99], v[172:175], 0
	v_exp_f32_e32 v198, v84
	v_exp_f32_e32 v199, v85
	v_add_f32_e32 v84, v64, v66
	v_add_f32_e32 v85, v65, v67
	v_exp_f32_e32 v80, v80
	v_add_f32_e32 v84, v68, v84
	v_add_f32_e32 v85, v69, v85
	v_exp_f32_e32 v81, v81
	v_add_f32_e32 v84, v70, v84
	v_add_f32_e32 v85, v71, v85
	v_mfma_f32_32x32x16_bf16 v[96:111], v[100:103], v[172:175], 0
	v_add_f32_e64 v84, v72, v84
	v_add_f32_e64 v85, v73, v85
	v_add_u32_e32 v242, v230, v226
	v_exp_f32_e32 v82, v82
	v_exp_f32_e32 v83, v83
	v_add_f32_e32 v84, v74, v84
	v_add_f32_e32 v85, v75, v85
	v_exp_f32_e32 v200, v86
	v_add_f32_e32 v84, v76, v84
	v_add_f32_e32 v85, v77, v85
	v_mfma_f32_32x32x16_bf16 v[112:127], v[234:237], v[168:171], v[112:127]
	v_exp_f32_e32 v201, v87
	v_add_f32_e32 v84, v78, v84
	v_add_f32_e32 v85, v79, v85
	v_exp_f32_e32 v88, v88
	v_exp_f32_e32 v89, v89
	v_add_f32_e32 v84, v80, v84
	v_add_f32_e32 v85, v81, v85
	v_exp_f32_e32 v90, v90
	v_exp_f32_e32 v91, v91
	v_mfma_f32_32x32x16_bf16 v[96:111], v[238:241], v[168:171], v[96:111]
	ds_read_b128 v[234:237], v233
	ds_read_b128 v[238:241], v233 offset:8192
	v_add_f32_e64 v84, v82, v84
	v_add_f32_e64 v85, v83, v85
	v_exp_f32_e32 v92, v92
	v_exp_f32_e32 v93, v93
	v_add_f32_e32 v84, v198, v84
	v_add_f32_e32 v85, v199, v85
	v_exp_f32_e32 v94, v94
	v_exp_f32_e32 v95, v95
	s_waitcnt lgkmcnt(0)
	v_mfma_f32_32x32x16_bf16 v[112:127], v[234:237], v[164:167], v[112:127]
	v_add_u32_e32 v234, v229, v210
	v_add_u32_e32 v235, v229, v212
	v_add_f32_e64 v84, v200, v84
	v_add_f32_e64 v85, v201, v85
	v_add_f32_e64 v84, v88, v84
	v_add_f32_e64 v85, v89, v85
	v_add_f32_e32 v84, v90, v84
	v_add_f32_e32 v85, v91, v85
	v_mfma_f32_32x32x16_bf16 v[96:111], v[238:241], v[164:167], v[96:111]
	ds_read_b128 v[236:239], v234
	ds_read_b128 v[244:247], v234 offset:8192
	v_add_f32_e64 v84, v92, v84
	v_add_f32_e64 v85, v93, v85
	v_add_f32_e64 v84, v94, v84
	v_add_f32_e64 v85, v95, v85
	v_pk_add_f32 v[196:197], v[84:85], v[84:85] op_sel:[0,1] op_sel_hi:[1,0]
	s_waitcnt lgkmcnt(0)
	v_mfma_f32_32x32x16_bf16 v[112:127], v[236:239], v[160:163], v[112:127]
	v_mfma_f32_32x32x16_bf16 v[96:111], v[244:247], v[160:163], v[96:111]
	ds_read_b128 v[236:239], v235
	ds_read_b128 v[244:247], v235 offset:8192
	s_waitcnt lgkmcnt(0)
	v_mfma_f32_32x32x16_bf16 v[112:127], v[236:239], v[156:159], v[112:127]
	v_add_u32_e32 v236, v229, v214
	v_add_u32_e32 v237, v229, v216
	v_mfma_f32_32x32x16_bf16 v[96:111], v[244:247], v[156:159], v[96:111]
	ds_read_b128 v[238:241], v236
	ds_read_b128 v[244:247], v236 offset:8192
	s_waitcnt lgkmcnt(0)
	v_mfma_f32_32x32x16_bf16 v[112:127], v[238:241], v[152:155], v[112:127]
	v_mfma_f32_32x32x16_bf16 v[96:111], v[244:247], v[152:155], v[96:111]
	ds_read_b128 v[238:241], v237
	ds_read_b128 v[244:247], v237 offset:8192
	s_waitcnt lgkmcnt(0)
	v_mfma_f32_32x32x16_bf16 v[112:127], v[238:241], v[148:151], v[112:127]
	v_add_u32_e32 v238, v229, v218
	v_add_u32_e32 v239, v230, v220
	v_add_u32_e32 v241, v230, v222
	v_add_u32_e32 v240, v230, v224
	v_mfma_f32_32x32x16_bf16 v[96:111], v[244:247], v[148:151], v[96:111]
	ds_read_b128 v[244:247], v238
	ds_read_b128 v[248:251], v238 offset:8192
	s_waitcnt lgkmcnt(0)
	v_mfma_f32_32x32x16_bf16 v[112:127], v[244:247], v[144:147], v[112:127]
	v_mfma_f32_32x32x16_bf16 v[96:111], v[248:251], v[144:147], v[96:111]
	ds_read_b128 v[244:247], v239
	ds_read_b128 v[248:251], v239 offset:4096
	s_waitcnt lgkmcnt(0)
	v_mfma_f32_32x32x16_bf16 v[112:127], v[244:247], v[140:143], v[112:127]
	v_mfma_f32_32x32x16_bf16 v[96:111], v[248:251], v[140:143], v[96:111]
	ds_read_b128 v[244:247], v241
	ds_read_b128 v[248:251], v241 offset:4096
	s_waitcnt lgkmcnt(0)
	v_mfma_f32_32x32x16_bf16 v[112:127], v[244:247], v[136:139], v[112:127]
	v_mfma_f32_32x32x16_bf16 v[96:111], v[248:251], v[136:139], v[96:111]
	ds_read_b128 v[244:247], v240
	ds_read_b128 v[248:251], v240 offset:4096
	s_waitcnt lgkmcnt(0)
	v_mfma_f32_32x32x16_bf16 v[112:127], v[244:247], v[132:135], v[112:127]
	v_mfma_f32_32x32x16_bf16 v[96:111], v[248:251], v[132:135], v[96:111]
	ds_read_b128 v[244:247], v242
	ds_read_b128 v[248:251], v242 offset:4096
	v_cvt_pk_bf16_f32 v84, v64, v65
	v_cvt_pk_bf16_f32 v85, v66, v67
	v_cvt_pk_bf16_f32 v86, v68, v69
	v_cvt_pk_bf16_f32 v87, v70, v71
	v_cvt_pk_bf16_f32 v72, v72, v73
	v_cvt_pk_bf16_f32 v73, v74, v75
	s_waitcnt lgkmcnt(0)
	v_mfma_f32_32x32x16_bf16 v[112:127], v[244:247], v[128:131], v[112:127]
	v_mov_b32_e32 v245, v196
	v_cvt_pk_bf16_f32 v74, v76, v77
	v_cvt_pk_bf16_f32 v75, v78, v79
	v_cvt_pk_bf16_f32 v76, v80, v81
	v_cvt_pk_bf16_f32 v77, v82, v83
	v_cvt_pk_bf16_f32 v78, v198, v199
	v_cvt_pk_bf16_f32 v79, v200, v201
	v_mfma_f32_32x32x16_bf16 v[96:111], v[248:251], v[128:131], v[96:111]
	v_cvt_pk_bf16_f32 v80, v88, v89
	v_cvt_pk_bf16_f32 v81, v90, v91
	v_cvt_pk_bf16_f32 v82, v92, v93
	v_cvt_pk_bf16_f32 v83, v94, v95
	s_nop 0
	v_permlane32_swap_b32_e32 v196, v245
	v_cndmask_b32_e64 v64, 0, 1, s[70:71]
	v_cmp_ne_u32_e64 s[4:5], 1, v64
	s_andn2_b64 vcc, exec, s[70:71]
	s_cbranch_vccnz .LBB0_604
	s_waitcnt vmcnt(0) lgkmcnt(0)
	s_barrier

; #define LAS __attribute__((address_space(3)))
; __device__ __forceinline__ void finishSM(f32x16& p0, f32x16& p1, float alpha, float& l_reg, bf16x8& pa0, bf16x8& pa1, bf16x8& pa2, bf16x8& pa3) {
; #pragma unroll
;     for (int r = 0; r < 16; ++r) p1[r] = __builtin_amdgcn_exp2f(p1[r]);
;     typedef float f32x2 __attribute__((ext_vector_type(2)));
;     f32x2 s2 = (f32x2){p0[0], p0[1]};
; #pragma unroll
;     for (int r = 2; r < 16; r += 2) s2 += (f32x2){p0[r], p0[r + 1]};
; #pragma unroll
;     for (int r = 0; r < 16; r += 2) s2 += (f32x2){p1[r], p1[r + 1]};
;     float ps = s2.x + s2.y;
;     { auto rr = __builtin_amdgcn_permlane32_swap(__float_as_uint(ps), __float_as_uint(ps), false, false);
;       ps = __uint_as_float(rr[0]) + __uint_as_float(rr[1]); }
;     l_reg = l_reg * alpha + ps;
;     ...
;     PK4(p0, 0, pa0); PK4(p0, 8, pa1); PK4(p1, 0, pa2); PK4(p1, 8, pa3);
;     ...
; }
; template <int MODE> __device__ __forceinline__ void qkt(f32x16& p0, f32x16& p1, const LAS unsigned char* Kt, const LAS unsigned char* Krt, const bf16x8* qr, int r32, int hi, int comp) {
;     p0 = f32x16{}; p1 = f32x16{};
;     constexpr int NDN = MODE ? 8 : 4;
; #pragma unroll
;     for (int d0 = 0; d0 < NDN; ++d0) { const int cb = ((MODE ? 0 : comp * 64) + d0 * 16 + hi * 8) * 2;
;         const bf16x8 b0 = *(const LAS bf16x8*)(Kt + KSWZ(r32, cb));
;         const bf16x8 b1 = *(const LAS bf16x8*)(Kt + KSWZ(32 + r32, cb));
;         p0 = __builtin_amdgcn_mfma_f32_32x32x16_bf16(b0, qr[d0], p0, 0, 0, 0);
;         p1 = __builtin_amdgcn_mfma_f32_32x32x16_bf16(b1, qr[d0], p1, 0, 0, 0); }
;     if constexpr (MODE == 1) {
; #pragma unroll
;         for (int d0 = 0; d0 < 4; ++d0) { const int cb = (d0 * 16 + hi * 8) * 2;
;             const bf16x8 b0 = *(const LAS bf16x8*)(Krt + KRSWZ(r32, cb));
;             const bf16x8 b1 = *(const LAS bf16x8*)(Krt + KRSWZ(32 + r32, cb));
;             p0 = __builtin_amdgcn_mfma_f32_32x32x16_bf16(b0, qr[8 + d0], p0, 0, 0, 0);
;             p1 = __builtin_amdgcn_mfma_f32_32x32x16_bf16(b1, qr[8 + d0], p1, 0, 0, 0); }
;     }
; }
.LBB0_614:
	s_nop 0
	ds_read_b128 v[80:83], v205 offset:49152
	ds_read_b128 v[84:87], v205 offset:57344
	ds_read_b128 v[248:251], v207 offset:49152
	ds_read_b128 v[198:201], v207 offset:57344
	ds_read_b128 v[234:237], v209 offset:49152
	ds_read_b128 v[238:241], v209 offset:57344
	v_exp_f32_e32 v112, v112
	v_exp_f32_e32 v113, v113
	s_waitcnt lgkmcnt(4)
	v_mfma_f32_32x32x16_bf16 v[96:111], v[80:83], v[172:175], 0
	v_exp_f32_e32 v114, v114
	v_exp_f32_e32 v115, v115
	v_exp_f32_e32 v122, v122
	v_exp_f32_e32 v123, v123
	v_exp_f32_e32 v124, v124
	v_exp_f32_e32 v125, v125
	v_exp_f32_e32 v126, v126
	v_mfma_f32_32x32x16_bf16 v[80:95], v[84:87], v[172:175], 0
	v_exp_f32_e32 v127, v127
	s_waitcnt lgkmcnt(2)
	v_mfma_f32_32x32x16_bf16 v[96:111], v[248:251], v[168:171], v[96:111]
	v_mfma_f32_32x32x16_bf16 v[80:95], v[198:201], v[168:171], v[80:95]
	ds_read_b128 v[198:201], v211 offset:49152
	ds_read_b128 v[248:251], v211 offset:57344
	s_waitcnt lgkmcnt(2)
	v_mfma_f32_32x32x16_bf16 v[96:111], v[234:237], v[164:167], v[96:111]
	v_mfma_f32_32x32x16_bf16 v[80:95], v[238:241], v[164:167], v[80:95]
	ds_read_b128 v[234:237], v213 offset:49152
	ds_read_b128 v[238:241], v213 offset:57344
	s_waitcnt lgkmcnt(2)
	v_mfma_f32_32x32x16_bf16 v[96:111], v[198:201], v[160:163], v[96:111]
	v_mfma_f32_32x32x16_bf16 v[80:95], v[248:251], v[160:163], v[80:95]
	ds_read_b128 v[198:201], v215 offset:49152
	ds_read_b128 v[248:251], v215 offset:57344
	s_waitcnt lgkmcnt(2)
	v_mfma_f32_32x32x16_bf16 v[96:111], v[234:237], v[156:159], v[96:111]
	v_mfma_f32_32x32x16_bf16 v[80:95], v[238:241], v[156:159], v[80:95]
	ds_read_b128 v[234:237], v217 offset:49152
	ds_read_b128 v[238:241], v217 offset:57344
	s_waitcnt lgkmcnt(2)
	v_mfma_f32_32x32x16_bf16 v[96:111], v[198:201], v[152:155], v[96:111]
	v_mfma_f32_32x32x16_bf16 v[80:95], v[248:251], v[152:155], v[80:95]
	ds_read_b128 v[198:201], v219 offset:49152
	ds_read_b128 v[248:251], v219 offset:57344
	s_waitcnt lgkmcnt(2)
	v_mfma_f32_32x32x16_bf16 v[96:111], v[234:237], v[148:151], v[96:111]
	v_mfma_f32_32x32x16_bf16 v[80:95], v[238:241], v[148:151], v[80:95]
	ds_read_b128 v[234:237], v221
	ds_read_b128 v[238:241], v221 offset:4096
	s_waitcnt lgkmcnt(2)
	v_mfma_f32_32x32x16_bf16 v[96:111], v[198:201], v[144:147], v[96:111]
	v_mfma_f32_32x32x16_bf16 v[80:95], v[248:251], v[144:147], v[80:95]
	ds_read_b128 v[198:201], v223
	ds_read_b128 v[248:251], v223 offset:4096
	s_waitcnt lgkmcnt(2)
	v_mfma_f32_32x32x16_bf16 v[96:111], v[234:237], v[140:143], v[96:111]
	v_mfma_f32_32x32x16_bf16 v[80:95], v[238:241], v[140:143], v[80:95]
	ds_read_b128 v[234:237], v225
	ds_read_b128 v[238:241], v225 offset:4096
	s_waitcnt lgkmcnt(2)
	v_mfma_f32_32x32x16_bf16 v[96:111], v[198:201], v[136:139], v[96:111]
	v_mfma_f32_32x32x16_bf16 v[80:95], v[248:251], v[136:139], v[80:95]
	ds_read_b128 v[198:201], v227
	ds_read_b128 v[248:251], v227 offset:4096
	s_waitcnt lgkmcnt(2)
	v_mfma_f32_32x32x16_bf16 v[96:111], v[234:237], v[132:135], v[96:111]
	v_mfma_f32_32x32x16_bf16 v[80:95], v[238:241], v[132:135], v[80:95]
	s_waitcnt lgkmcnt(0)
	v_mfma_f32_32x32x16_bf16 v[96:111], v[198:201], v[128:131], v[96:111]
	v_exp_f32_e32 v198, v116
	v_exp_f32_e32 v199, v117
	v_add_f32_e32 v116, v64, v66
	v_add_f32_e32 v117, v65, v67
	v_exp_f32_e32 v200, v118
	v_add_f32_e32 v116, v68, v116
	v_add_f32_e32 v117, v69, v117
	v_exp_f32_e32 v201, v119
	v_add_f32_e32 v116, v70, v116
	v_add_f32_e32 v117, v71, v117
	v_mfma_f32_32x32x16_bf16 v[80:95], v[248:251], v[128:131], v[80:95]
	v_add_f32_e64 v116, v72, v116
	v_add_f32_e64 v117, v73, v117
	v_exp_f32_e32 v248, v120
	v_add_f32_e32 v116, v74, v116
	v_add_f32_e32 v117, v75, v117
	v_exp_f32_e32 v249, v121
	v_add_f32_e32 v116, v76, v116
	v_add_f32_e32 v117, v77, v117
	v_add_f32_e32 v116, v78, v116
	v_add_f32_e32 v117, v79, v117
	v_add_f32_e32 v116, v112, v116
	v_add_f32_e32 v117, v113, v117
	v_add_f32_e32 v116, v114, v116
	v_add_f32_e32 v117, v115, v117
	v_add_f32_e32 v116, v198, v116
	v_add_f32_e32 v117, v199, v117
	v_add_f32_e32 v116, v200, v116
	v_add_f32_e32 v117, v201, v117
	v_add_f32_e32 v116, v248, v116
	v_add_f32_e32 v117, v249, v117
	v_add_f32_e32 v116, v122, v116
	v_add_f32_e32 v117, v123, v117
	v_add_f32_e32 v116, v124, v116
	v_add_f32_e32 v117, v125, v117
	v_add_f32_e32 v116, v126, v116
	v_add_f32_e32 v117, v127, v117
	v_pk_add_f32 v[120:121], v[116:117], v[116:117] op_sel:[0,1] op_sel_hi:[1,0]
	v_cvt_pk_bf16_f32 v116, v64, v65
	v_cvt_pk_bf16_f32 v117, v66, v67
	v_cvt_pk_bf16_f32 v118, v68, v69
	v_cvt_pk_bf16_f32 v119, v70, v71
	v_cvt_pk_bf16_f32 v72, v72, v73
	s_nop 0
	v_mov_b32_e32 v121, v120
	v_cvt_pk_bf16_f32 v73, v74, v75
	v_cvt_pk_bf16_f32 v74, v76, v77
	v_cvt_pk_bf16_f32 v75, v78, v79
	v_cvt_pk_bf16_f32 v76, v112, v113
	v_cvt_pk_bf16_f32 v77, v114, v115
	v_cvt_pk_bf16_f32 v78, v198, v199
	v_cvt_pk_bf16_f32 v79, v200, v201
	v_cvt_pk_bf16_f32 v112, v248, v249
	v_cvt_pk_bf16_f32 v113, v122, v123
	v_cvt_pk_bf16_f32 v114, v124, v125
	v_cvt_pk_bf16_f32 v115, v126, v127
	s_nop 1
	v_permlane32_swap_b32_e32 v120, v121
	s_and_b64 vcc, exec, s[4:5]
	s_cbranch_vccnz .LBB0_616
	s_waitcnt vmcnt(0) lgkmcnt(0)
	s_barrier
